# pooling item MFMA part: the 16 weight-fragment loads issued before the barrier (one round trip instead of four)
# baseline (speedup 1.0000x reference)
.LBB0_674:
	s_or_b64 exec, exec, s[4:5]
	v_bfe_u32 v52, v0, 4, 2
	v_and_b32_e32 v6, 0xffffffcf, v0
	v_readlane_b32 s4, v255, 43
	v_lshl_add_u32 v2, v0, 1, 0
	v_lshlrev_b32_e32 v16, 4, v52
	v_readlane_b32 s5, v255, 44
	v_ashrrev_i32_e32 v7, 31, v6
	ds_write_b16 v2, v1 offset:65520
	v_lshl_add_u64 v[22:23], s[4:5], 0, v[16:17]
	v_lshlrev_b64 v[2:3], 8, v[6:7]
	v_and_b32_e32 v53, 15, v0
	v_and_b32_e32 v54, 64, v0
	v_and_b32_e32 v50, 0xffffff80, v0
	v_lshl_add_u64 v[4:5], v[22:23], 0, v[2:3]
	v_or_b32_e32 v2, 16, v6
	v_or_b32_e32 v6, 32, v6
	v_or_b32_e32 v0, 48, v0
	v_ashrrev_i32_e32 v3, 31, v2
	v_ashrrev_i32_e32 v7, 31, v6
	v_ashrrev_i32_e32 v1, 31, v0
	v_lshlrev_b64 v[2:3], 8, v[2:3]
	v_lshlrev_b64 v[6:7], 8, v[6:7]
	v_lshlrev_b64 v[0:1], 8, v[0:1]
	v_lshl_add_u64 v[2:3], v[22:23], 0, v[2:3]
	v_lshl_add_u64 v[6:7], v[22:23], 0, v[6:7]
	v_lshl_add_u64 v[0:1], v[22:23], 0, v[0:1]
	global_load_dwordx4 v[138:141], v[4:5], off
	global_load_dwordx4 v[142:145], v[6:7], off
	global_load_dwordx4 v[146:149], v[2:3], off
	global_load_dwordx4 v[150:153], v[0:1], off
	global_load_dwordx4 v[154:157], v[4:5], off offset:64
	global_load_dwordx4 v[158:161], v[2:3], off offset:64
	global_load_dwordx4 v[162:165], v[6:7], off offset:64
	global_load_dwordx4 v[166:169], v[0:1], off offset:64
	global_load_dwordx4 v[170:173], v[4:5], off offset:128
	global_load_dwordx4 v[174:177], v[2:3], off offset:128
	global_load_dwordx4 v[178:181], v[6:7], off offset:128
	global_load_dwordx4 v[182:185], v[0:1], off offset:128
	global_load_dwordx4 v[186:189], v[4:5], off offset:192
	global_load_dwordx4 v[190:193], v[2:3], off offset:192
	global_load_dwordx4 v[194:197], v[6:7], off offset:192
	global_load_dwordx4 v[208:211], v[0:1], off offset:192
	s_waitcnt lgkmcnt(0)
	s_barrier
	s_waitcnt vmcnt(0)
	v_mov_b64_e32 v[8:9], v[138:139]
	v_mov_b64_e32 v[10:11], v[140:141]
	v_mov_b64_e32 v[18:19], v[142:143]
	v_mov_b64_e32 v[20:21], v[144:145]
	v_mov_b64_e32 v[12:13], v[146:147]
	v_mov_b64_e32 v[14:15], v[148:149]
	v_mov_b64_e32 v[22:23], v[150:151]
	v_mov_b64_e32 v[24:25], v[152:153]
	v_lshl_add_u32 v26, v50, 1, 0
	v_mul_u32_u24_e32 v27, 0x410, v53
	v_add3_u32 v16, v26, v16, v27
	ds_read_b128 v[26:29], v16
	ds_read_b128 v[42:45], v16 offset:16640
	ds_read_b128 v[64:67], v16 offset:33280
	ds_read_b128 v[84:87], v16 offset:49920
	v_readlane_b32 s8, v255, 37
	v_readlane_b32 s9, v255, 38
	v_ashrrev_i32_e32 v51, 31, v50
	v_lshl_or_b32 v52, v52, 2, v54
	v_or_b32_e32 v53, s18, v53
	s_waitcnt vmcnt(0) lgkmcnt(0)
	v_mfma_f32_16x16x32_bf16 v[30:33], v[8:11], v[26:29], 0
	v_mfma_f32_16x16x32_bf16 v[34:37], v[12:15], v[26:29], 0
	v_mfma_f32_16x16x32_bf16 v[38:41], v[18:21], v[26:29], 0
	v_mfma_f32_16x16x32_bf16 v[26:29], v[22:25], v[26:29], 0
	v_mfma_f32_16x16x32_bf16 v[46:49], v[8:11], v[42:45], 0
	v_mfma_f32_16x16x32_bf16 v[56:59], v[12:15], v[42:45], 0
	v_mfma_f32_16x16x32_bf16 v[60:63], v[18:21], v[42:45], 0
	v_mfma_f32_16x16x32_bf16 v[42:45], v[22:25], v[42:45], 0
	v_mfma_f32_16x16x32_bf16 v[68:71], v[8:11], v[64:67], 0
	v_mfma_f32_16x16x32_bf16 v[72:75], v[12:15], v[64:67], 0
	v_mfma_f32_16x16x32_bf16 v[80:83], v[18:21], v[64:67], 0
	v_mfma_f32_16x16x32_bf16 v[64:67], v[22:25], v[64:67], 0
	v_mfma_f32_16x16x32_bf16 v[8:11], v[8:11], v[84:87], 0
	v_mfma_f32_16x16x32_bf16 v[12:15], v[12:15], v[84:87], 0
	v_mfma_f32_16x16x32_bf16 v[18:21], v[18:21], v[84:87], 0
	v_mfma_f32_16x16x32_bf16 v[22:25], v[22:25], v[84:87], 0
	v_mov_b64_e32 v[84:85], v[154:155]
	v_mov_b64_e32 v[86:87], v[156:157]
	v_mov_b64_e32 v[88:89], v[158:159]
	v_mov_b64_e32 v[90:91], v[160:161]
	v_mov_b64_e32 v[92:93], v[162:163]
	v_mov_b64_e32 v[94:95], v[164:165]
	v_mov_b64_e32 v[96:97], v[166:167]
	v_mov_b64_e32 v[98:99], v[168:169]
	ds_read_b128 v[100:103], v16 offset:64
	s_waitcnt vmcnt(0) lgkmcnt(0)
	v_mfma_f32_16x16x32_bf16 v[30:33], v[84:87], v[100:103], v[30:33]
	v_mfma_f32_16x16x32_bf16 v[34:37], v[88:91], v[100:103], v[34:37]
	v_mfma_f32_16x16x32_bf16 v[38:41], v[92:95], v[100:103], v[38:41]
	v_mfma_f32_16x16x32_bf16 v[26:29], v[96:99], v[100:103], v[26:29]
	ds_read_b128 v[100:103], v16 offset:16704
	s_waitcnt lgkmcnt(0)
	v_mfma_f32_16x16x32_bf16 v[46:49], v[84:87], v[100:103], v[46:49]
	v_mfma_f32_16x16x32_bf16 v[56:59], v[88:91], v[100:103], v[56:59]
	v_mfma_f32_16x16x32_bf16 v[60:63], v[92:95], v[100:103], v[60:63]
	v_mfma_f32_16x16x32_bf16 v[42:45], v[96:99], v[100:103], v[42:45]
	ds_read_b128 v[100:103], v16 offset:33344
	s_waitcnt lgkmcnt(0)
	v_mfma_f32_16x16x32_bf16 v[68:71], v[84:87], v[100:103], v[68:71]
	v_mfma_f32_16x16x32_bf16 v[72:75], v[88:91], v[100:103], v[72:75]
	v_mfma_f32_16x16x32_bf16 v[80:83], v[92:95], v[100:103], v[80:83]
	v_mfma_f32_16x16x32_bf16 v[64:67], v[96:99], v[100:103], v[64:67]
	ds_read_b128 v[100:103], v16 offset:49984
	s_waitcnt lgkmcnt(0)
	v_mfma_f32_16x16x32_bf16 v[8:11], v[84:87], v[100:103], v[8:11]
	v_mfma_f32_16x16x32_bf16 v[12:15], v[88:91], v[100:103], v[12:15]
	v_mfma_f32_16x16x32_bf16 v[18:21], v[92:95], v[100:103], v[18:21]
	v_mfma_f32_16x16x32_bf16 v[22:25], v[96:99], v[100:103], v[22:25]
	v_mov_b64_e32 v[84:85], v[170:171]
	v_mov_b64_e32 v[86:87], v[172:173]
	v_mov_b64_e32 v[88:89], v[174:175]
	v_mov_b64_e32 v[90:91], v[176:177]
	v_mov_b64_e32 v[92:93], v[178:179]
	v_mov_b64_e32 v[94:95], v[180:181]
	v_mov_b64_e32 v[96:97], v[182:183]
	v_mov_b64_e32 v[98:99], v[184:185]
	ds_read_b128 v[100:103], v16 offset:128
	s_waitcnt vmcnt(0) lgkmcnt(0)
	v_mfma_f32_16x16x32_bf16 v[30:33], v[84:87], v[100:103], v[30:33]
	v_mfma_f32_16x16x32_bf16 v[34:37], v[88:91], v[100:103], v[34:37]
	v_mfma_f32_16x16x32_bf16 v[38:41], v[92:95], v[100:103], v[38:41]
	v_mfma_f32_16x16x32_bf16 v[100:103], v[96:99], v[100:103], v[26:29]
	s_nop 2
	ds_read_b128 v[26:29], v16 offset:16768
	s_waitcnt lgkmcnt(0)
	v_mfma_f32_16x16x32_bf16 v[46:49], v[84:87], v[26:29], v[46:49]
	v_mfma_f32_16x16x32_bf16 v[56:59], v[88:91], v[26:29], v[56:59]
	v_mfma_f32_16x16x32_bf16 v[60:63], v[92:95], v[26:29], v[60:63]
	v_mfma_f32_16x16x32_bf16 v[42:45], v[96:99], v[26:29], v[42:45]
	ds_read_b128 v[26:29], v16 offset:33408
	s_waitcnt lgkmcnt(0)
	v_mfma_f32_16x16x32_bf16 v[68:71], v[84:87], v[26:29], v[68:71]
	v_mfma_f32_16x16x32_bf16 v[72:75], v[88:91], v[26:29], v[72:75]
	v_mfma_f32_16x16x32_bf16 v[80:83], v[92:95], v[26:29], v[80:83]
	v_mfma_f32_16x16x32_bf16 v[64:67], v[96:99], v[26:29], v[64:67]
	ds_read_b128 v[26:29], v16 offset:50048
	s_waitcnt lgkmcnt(0)
	v_mfma_f32_16x16x32_bf16 v[18:21], v[92:95], v[26:29], v[18:21]
	v_mfma_f32_16x16x32_bf16 v[92:95], v[96:99], v[26:29], v[22:25]
	v_mov_b64_e32 v[96:97], v[186:187]
	v_mov_b64_e32 v[98:99], v[188:189]
	v_mov_b64_e32 v[104:105], v[190:191]
	v_mov_b64_e32 v[106:107], v[192:193]
	v_mov_b64_e32 v[108:109], v[194:195]
	v_mov_b64_e32 v[110:111], v[196:197]
	s_nop 0
	v_mov_b64_e32 v[0:1], v[208:209]
	v_mov_b64_e32 v[2:3], v[210:211]
	ds_read_b128 v[4:7], v16 offset:192
	v_mfma_f32_16x16x32_bf16 v[84:87], v[84:87], v[26:29], v[8:11]
	v_mfma_f32_16x16x32_bf16 v[88:91], v[88:91], v[26:29], v[12:15]
	s_waitcnt vmcnt(0) lgkmcnt(0)
	v_mfma_f32_16x16x32_bf16 v[112:115], v[96:99], v[4:7], v[30:33]
	v_mfma_f32_16x16x32_bf16 v[34:37], v[104:107], v[4:7], v[34:37]
	v_mfma_f32_16x16x32_bf16 v[26:29], v[108:111], v[4:7], v[38:41]
	v_mfma_f32_16x16x32_bf16 v[8:11], v[0:3], v[4:7], v[100:103]
	ds_read_b128 v[4:7], v16 offset:16832
	s_waitcnt lgkmcnt(0)
	v_mfma_f32_16x16x32_bf16 v[100:103], v[96:99], v[4:7], v[46:49]
	v_mfma_f32_16x16x32_bf16 v[38:41], v[104:107], v[4:7], v[56:59]
	v_mfma_f32_16x16x32_bf16 v[30:33], v[108:111], v[4:7], v[60:63]
	s_nop 1
	ds_read_b128 v[56:59], v16 offset:50112
	v_mfma_f32_16x16x32_bf16 v[12:15], v[0:3], v[4:7], v[42:45]
	ds_read_b128 v[4:7], v16 offset:33472
	s_mov_b32 s4, 0
	s_ashr_i32 s5, s4, 31
	s_lshl_b64 s[4:5], s[4:5], 3
	s_add_u32 s4, s0, s4
	s_addc_u32 s5, s1, s5
	s_load_dwordx2 s[4:5], s[4:5], 0xb8
	s_waitcnt lgkmcnt(0)
	v_mfma_f32_16x16x32_bf16 v[60:63], v[96:99], v[4:7], v[68:71]
	v_lshlrev_b32_e32 v16, 2, v52
	s_add_u32 s4, s4, s8
	s_addc_u32 s5, s5, s9
	v_mfma_f32_16x16x32_bf16 v[42:45], v[104:107], v[4:7], v[72:75]
	v_mfma_f32_16x16x32_bf16 v[22:25], v[108:111], v[4:7], v[80:83]
	v_mfma_f32_16x16x32_bf16 v[4:7], v[0:3], v[4:7], v[64:67]
	v_mfma_f32_16x16x32_bf16 v[64:67], v[96:99], v[56:59], v[84:87]
	v_mfma_f32_16x16x32_bf16 v[46:49], v[104:107], v[56:59], v[88:91]
	v_mfma_f32_16x16x32_bf16 v[18:21], v[108:111], v[56:59], v[18:21]
	v_mfma_f32_16x16x32_bf16 v[0:3], v[0:3], v[56:59], v[92:95]
	v_lshl_add_u64 v[56:57], v[50:51], 2, s[4:5]
	v_lshl_add_u64 v[54:55], v[56:57], 0, v[16:17]
	global_load_dwordx4 v[68:71], v[54:55], off
	v_readlane_b32 s4, v255, 45
	v_readlane_b32 s5, v255, 46
	v_lshlrev_b32_e32 v16, 1, v52
	s_waitcnt vmcnt(0)
	v_mul_f32_e32 v52, v103, v71
	v_lshl_add_u64 v[50:51], v[50:51], 1, s[4:5]
	v_lshl_add_u64 v[56:57], v[50:51], 0, v[16:17]
	v_mul_f32_e32 v16, v112, v68
	v_mul_f32_e32 v50, v113, v69
	v_cvt_pk_bf16_f32 v50, v16, v50
	v_mul_f32_e32 v16, v114, v70
	v_mul_f32_e32 v51, v115, v71
	v_cvt_pk_bf16_f32 v51, v16, v51
	v_lshlrev_b32_e32 v16, 10, v53
	v_lshl_add_u64 v[58:59], v[56:57], 0, v[16:17]
	global_store_dwordx2 v[58:59], v[50:51], off
	v_mul_f32_e32 v50, v100, v68
	v_mul_f32_e32 v51, v101, v69
	v_cvt_pk_bf16_f32 v50, v50, v51
	v_mul_f32_e32 v51, v102, v70
	v_cvt_pk_bf16_f32 v51, v51, v52
	v_or_b32_e32 v52, 0x4000, v16
	v_mov_b32_e32 v53, v17
	v_lshl_add_u64 v[72:73], v[56:57], 0, v[52:53]
	global_store_dwordx2 v[72:73], v[50:51], off
	v_mul_f32_e32 v50, v60, v68
	v_mul_f32_e32 v51, v61, v69
	v_cvt_pk_bf16_f32 v60, v50, v51
	v_mul_f32_e32 v50, v62, v70
	v_mul_f32_e32 v51, v63, v71
	v_cvt_pk_bf16_f32 v61, v50, v51
	v_or_b32_e32 v50, 0x8000, v16
	v_mov_b32_e32 v51, v17
	v_lshl_add_u64 v[62:63], v[56:57], 0, v[50:51]
	global_store_dwordx2 v[62:63], v[60:61], off
	v_mul_f32_e32 v60, v64, v68
	v_mul_f32_e32 v61, v65, v69
	v_cvt_pk_bf16_f32 v60, v60, v61
	v_mul_f32_e32 v61, v66, v70
	v_mul_f32_e32 v62, v67, v71
	v_or_b32_e32 v16, 0xc000, v16
	v_cvt_pk_bf16_f32 v61, v61, v62
	v_lshl_add_u64 v[62:63], v[56:57], 0, v[16:17]
	global_store_dwordx2 v[62:63], v[60:61], off
	global_load_dwordx4 v[60:63], v[54:55], off offset:64
	v_lshl_add_u64 v[64:65], v[56:57], 0, 32
	s_mov_b64 s[4:5], 0x60
	s_waitcnt vmcnt(0)
	v_mul_f32_e32 v34, v34, v60
	v_mul_f32_e32 v35, v35, v61
	v_cvt_pk_bf16_f32 v34, v34, v35
	v_mul_f32_e32 v35, v36, v62
	v_mul_f32_e32 v36, v37, v63
	v_cvt_pk_bf16_f32 v35, v35, v36
	global_store_dwordx2 v[58:59], v[34:35], off offset:32
	v_mul_f32_e32 v34, v38, v60
	v_mul_f32_e32 v35, v39, v61
	v_cvt_pk_bf16_f32 v34, v34, v35
	v_mul_f32_e32 v35, v40, v62
	v_mul_f32_e32 v36, v41, v63
	v_cvt_pk_bf16_f32 v35, v35, v36
	v_lshl_add_u64 v[36:37], v[64:65], 0, v[52:53]
	global_store_dwordx2 v[36:37], v[34:35], off
	v_mul_f32_e32 v34, v42, v60
	v_mul_f32_e32 v35, v43, v61
	v_cvt_pk_bf16_f32 v34, v34, v35
	v_mul_f32_e32 v35, v44, v62
	v_mul_f32_e32 v36, v45, v63
	v_cvt_pk_bf16_f32 v35, v35, v36
	v_lshl_add_u64 v[36:37], v[64:65], 0, v[50:51]
	global_store_dwordx2 v[36:37], v[34:35], off
	v_mul_f32_e32 v34, v46, v60
	v_mul_f32_e32 v35, v47, v61
	v_cvt_pk_bf16_f32 v34, v34, v35
	v_mul_f32_e32 v35, v48, v62
	v_mul_f32_e32 v36, v49, v63
	v_cvt_pk_bf16_f32 v35, v35, v36
	v_lshl_add_u64 v[36:37], v[64:65], 0, v[16:17]
	global_store_dwordx2 v[36:37], v[34:35], off
	global_load_dwordx4 v[34:37], v[54:55], off offset:128
	v_lshl_add_u64 v[38:39], v[56:57], 0, 64
	s_waitcnt vmcnt(0)
	v_mul_f32_e32 v26, v26, v34
	v_mul_f32_e32 v27, v27, v35
	v_cvt_pk_bf16_f32 v26, v26, v27
	v_mul_f32_e32 v27, v28, v36
	v_mul_f32_e32 v28, v29, v37
	v_cvt_pk_bf16_f32 v27, v27, v28
	global_store_dwordx2 v[58:59], v[26:27], off offset:64
	v_mul_f32_e32 v26, v30, v34
	v_mul_f32_e32 v27, v31, v35
	v_mul_f32_e32 v22, v22, v34
	v_mul_f32_e32 v23, v23, v35
	v_mul_f32_e32 v18, v18, v34
	v_mul_f32_e32 v19, v19, v35
	v_cvt_pk_bf16_f32 v26, v26, v27
	v_mul_f32_e32 v27, v32, v36
	v_mul_f32_e32 v28, v33, v37
	v_cvt_pk_bf16_f32 v22, v22, v23
	v_mul_f32_e32 v23, v24, v36
	v_mul_f32_e32 v24, v25, v37
	v_cvt_pk_bf16_f32 v18, v18, v19
	v_mul_f32_e32 v19, v20, v36
	v_mul_f32_e32 v20, v21, v37
	v_cvt_pk_bf16_f32 v27, v27, v28
	v_lshl_add_u64 v[28:29], v[38:39], 0, v[52:53]
	v_cvt_pk_bf16_f32 v23, v23, v24
	v_lshl_add_u64 v[24:25], v[38:39], 0, v[50:51]
	v_cvt_pk_bf16_f32 v19, v19, v20
	v_lshl_add_u64 v[20:21], v[38:39], 0, v[16:17]
	global_store_dwordx2 v[28:29], v[26:27], off
	global_store_dwordx2 v[24:25], v[22:23], off
	global_store_dwordx2 v[20:21], v[18:19], off
	global_load_dwordx4 v[18:21], v[54:55], off offset:192
	v_lshl_add_u64 v[22:23], v[56:57], 0, s[4:5]
	s_waitcnt vmcnt(0)
	v_mul_f32_e32 v8, v8, v18
	v_mul_f32_e32 v9, v9, v19
	v_cvt_pk_bf16_f32 v8, v8, v9
	v_mul_f32_e32 v9, v10, v20
	v_mul_f32_e32 v10, v11, v21
	v_cvt_pk_bf16_f32 v9, v9, v10
	global_store_dwordx2 v[58:59], v[8:9], off offset:96
	v_mul_f32_e32 v8, v12, v18
	v_mul_f32_e32 v9, v13, v19
	v_mul_f32_e32 v4, v4, v18
	v_mul_f32_e32 v5, v5, v19
	v_mul_f32_e32 v0, v0, v18
	v_mul_f32_e32 v1, v1, v19
	v_cvt_pk_bf16_f32 v8, v8, v9
	v_mul_f32_e32 v9, v14, v20
	v_mul_f32_e32 v10, v15, v21
	v_cvt_pk_bf16_f32 v4, v4, v5
	v_mul_f32_e32 v5, v6, v20
	v_mul_f32_e32 v6, v7, v21
	v_cvt_pk_bf16_f32 v0, v0, v1
	v_mul_f32_e32 v1, v2, v20
	v_mul_f32_e32 v2, v3, v21
	v_cvt_pk_bf16_f32 v9, v9, v10
	v_lshl_add_u64 v[10:11], v[22:23], 0, v[52:53]
	v_cvt_pk_bf16_f32 v5, v5, v6
	v_lshl_add_u64 v[6:7], v[22:23], 0, v[50:51]
	v_cvt_pk_bf16_f32 v1, v1, v2
	v_lshl_add_u64 v[2:3], v[22:23], 0, v[16:17]
	global_store_dwordx2 v[10:11], v[8:9], off
	global_store_dwordx2 v[6:7], v[4:5], off
	global_store_dwordx2 v[2:3], v[0:1], off
	s_waitcnt lgkmcnt(0)
	s_barrier
